# baseline (speedup 1.0000x reference)
; __device__ void peer_phase(const Params& p) {
;     ...
;         hq[k] = (int)(((u32)q0 & 0xFFu) | (((u32)q1 & 0xFFu) << 8) | (((u32)q2 & 0xFFu) << 16) | (((u32)q3 & 0xFFu) << 24));
;       }
;       hsum = wave_sum_i(hs);
;     }
;     int eid[2];
;     float gg[2];
;     eid[0] = eidn0; eid[1] = eidn1;
;     if (tok + nw < T_TOK) { eidn0 = p.idx[(size_t)(tok + nw) * 128 + lane]; eidn1 = p.idx[(size_t)(tok + nw) * 128 + 64 + lane]; }
;     gg[0] = p.gate[(size_t)tok * 128 + lane];
;     gg[1] = p.gate[(size_t)tok * 128 + 64 + lane];
; #pragma unroll
;     for (int hf = 0; hf < 2; ++hf) {
;       const float sv = gg[hf] * rinv;
;       float m = sv;
; #pragma unroll
;       for (int o = 8; o >= 1; o >>= 1) m = fmaxf(m, __shfl_xor(m, o));
;       const float ev = __expf(sv - m);
;       float sm = ev;
; #pragma unroll
;       for (int o = 8; o >= 1; o >>= 1) sm += __shfl_xor(sm, o);
;       gg[hf] = ev / sm;
;     }
;     const float ds0 = p.dscale[eid[0]], ds1 = p.dscale[eid[1]];
;     const float us0 = p.uscale[eid[0]], us1 = p.uscale[eid[1]];
; #pragma unroll
;     for (int hf = 0; hf < 2; ++hf) {
;       int acti = 0;
;       for (int e = 0; e < 64; e += 16) {
;         uint4 d[16];
; #pragma unroll
;         for (int u = 0; u < 16; ++u) {
;           const int id = __builtin_amdgcn_readlane(eid[hf], e + u);
;           d[u] = ((const uint4*)(down4 + (size_t)id * 1024))[lane];
;         }
.LBB0_850:
	s_or_b64 exec, exec, s[4:5]
	v_ashrrev_i32_e32 v81, 31, v80
	v_lshlrev_b64 v[38:39], 9, v[80:81]
	v_lshl_add_u64 v[38:39], v[72:73], 0, v[38:39]
	global_load_dword v40, v[38:39], off
	global_load_dword v41, v[38:39], off offset:256
	v_ashrrev_i32_e32 v87, 31, v86
	v_readlane_b32 s36, v253, 55
	s_waitcnt lgkmcnt(1)
	v_add_f32_e32 v38, v0, v1
	v_ashrrev_i32_e32 v83, 31, v82
	v_lshlrev_b64 v[0:1], 2, v[86:87]
	v_readlane_b32 s46, v254, 1
	v_readlane_b32 s47, v254, 2
	v_lshlrev_b32_e32 v42, 16, v26
	v_lshlrev_b32_e32 v43, 24, v27
	v_lshlrev_b32_e32 v44, 8, v28
	v_lshlrev_b32_e32 v45, 16, v29
	v_lshlrev_b64 v[26:27], 2, v[82:83]
	v_readlane_b32 s48, v254, 3
	v_readlane_b32 s49, v254, 4
	v_lshl_add_u64 v[28:29], s[46:47], 0, v[0:1]
	v_lshlrev_b32_e32 v39, 8, v16
	v_lshlrev_b32_e32 v46, 24, v30
	v_lshlrev_b32_e32 v47, 8, v31
	v_lshlrev_b32_e32 v48, 16, v32
	v_lshlrev_b32_e32 v49, 24, v33
	v_lshl_add_u64 v[30:31], s[46:47], 0, v[26:27]
	v_lshl_add_u64 v[32:33], s[48:49], 0, v[0:1]
	v_lshl_add_u64 v[26:27], s[48:49], 0, v[26:27]
	global_load_dword v16, v[28:29], off
	global_load_dword v3, v[30:31], off
	global_load_dword v1, v[32:33], off
	global_load_dword v0, v[26:27], off
	v_lshlrev_b32_e32 v26, 16, v17
	v_fmamk_f32 v17, v38, 0x3a000000, v98
	s_and_b64 s[0:1], exec, vcc
	v_perm_b32 v28, v44, v5, s11
	v_mul_f32_e32 v5, 0x4b800000, v17
	v_cmp_gt_f32_e32 vcc, s10, v17
	v_perm_b32 v30, v47, v6, s11
	v_lshlrev_b32_e32 v34, 8, v34
	v_cndmask_b32_e32 v5, v17, v5, vcc
	v_rsq_f32_e32 v5, v5
	v_lshlrev_b32_e32 v37, 8, v37
	v_perm_b32 v32, v34, v7, s11
	v_perm_b32 v34, v37, v8, s11
	v_mul_f32_e32 v6, 0x45800000, v5
	v_cndmask_b32_e32 v17, v5, v6, vcc
	v_lshlrev_b32_e32 v35, 16, v35
	v_lshlrev_b32_e32 v2, 8, v2
	v_and_b32_e32 v33, 0xff0000, v35
	v_perm_b32 v35, v2, v11, s11
	v_lshlrev_b32_e32 v19, 8, v19
	v_perm_b32 v19, v19, v9, s11
	v_perm_b32 v4, v39, v4, s11
	v_and_b32_e32 v27, 0xff0000, v42
	v_lshlrev_b32_e32 v22, 8, v22
	v_perm_b32 v22, v22, v10, s11
	v_lshlrev_b32_e32 v20, 16, v20
	v_lshlrev_b32_e32 v18, 24, v18
	v_lshlrev_b32_e32 v21, 24, v21
	v_and_b32_e32 v26, 0xff0000, v26
	v_and_b32_e32 v20, 0xff0000, v20
	v_lshlrev_b32_e32 v23, 16, v23
	v_lshlrev_b32_e32 v25, 16, v25
	v_lshlrev_b32_e32 v36, 24, v36
	v_lshlrev_b32_e32 v24, 24, v24
	v_and_b32_e32 v29, 0xff0000, v45
	v_and_b32_e32 v31, 0xff0000, v48
	v_and_b32_e32 v23, 0xff0000, v23
	v_and_b32_e32 v25, 0xff0000, v25
	v_lshlrev_b32_e32 v12, 24, v12
	s_or_b64 s[2:3], s[0:1], s[2:3]
	v_or3_b32 v12, v35, v25, v12
	s_mov_b32 s4, 0
	v_readlane_b32 s37, v253, 56
	v_readlane_b32 s38, v253, 57
	v_readlane_b32 s39, v253, 58
	v_readlane_b32 s40, v253, 59
	v_readlane_b32 s41, v253, 60
	v_readlane_b32 s42, v253, 61
	v_readlane_b32 s43, v253, 62
	v_readlane_b32 s44, v253, 63
	v_readlane_b32 s45, v254, 0
	v_readlane_b32 s50, v254, 5
	v_readlane_b32 s51, v254, 6
	s_waitcnt vmcnt(5)
	v_mul_f32_e32 v5, v17, v40
	s_waitcnt vmcnt(4)
	v_mul_f32_e32 v6, v17, v41
	ds_bpermute_b32 v7, v91, v5
	ds_bpermute_b32 v8, v91, v6
	s_waitcnt lgkmcnt(1)
	v_max_f32_e32 v7, v7, v7
	s_waitcnt lgkmcnt(0)
	v_max_f32_e32 v8, v8, v8
	v_max_f32_e32 v5, v5, v7
	v_max_f32_e32 v6, v6, v8
	ds_bpermute_b32 v7, v92, v5
	ds_bpermute_b32 v8, v92, v6
	s_waitcnt lgkmcnt(1)
	v_max_f32_e32 v2, v7, v7
	s_waitcnt lgkmcnt(0)
	v_max_f32_e32 v7, v8, v8
	v_max_f32_e32 v2, v5, v2
	v_max_f32_e32 v7, v6, v7
	ds_bpermute_b32 v8, v93, v2
	ds_bpermute_b32 v9, v93, v7
	v_or3_b32 v5, v4, v27, v43
	v_or3_b32 v6, v28, v29, v46
	s_waitcnt lgkmcnt(1)
	v_max_f32_e32 v4, v8, v8
	s_waitcnt lgkmcnt(0)
	v_max_f32_e32 v8, v9, v9
	v_max_f32_e32 v2, v2, v4
	v_max_f32_e32 v4, v7, v8
	ds_bpermute_b32 v10, v94, v2
	ds_bpermute_b32 v11, v94, v4
	v_or3_b32 v9, v34, v26, v18
	v_or3_b32 v7, v30, v31, v49
	v_or3_b32 v8, v32, v33, v36
	s_waitcnt lgkmcnt(1)
	v_max_f32_e32 v10, v10, v10
	s_waitcnt lgkmcnt(0)
	v_max_f32_e32 v11, v11, v11
	v_max_f32_e32 v2, v2, v10
	v_max_f32_e32 v4, v4, v11
	v_fma_f32 v2, v17, v40, -v2
	v_fma_f32 v4, v17, v41, -v4
	v_mul_f32_e32 v2, 0x3fb8aa3b, v2
	v_mul_f32_e32 v10, 0x3fb8aa3b, v4
	v_exp_f32_e32 v4, v2
	v_exp_f32_e32 v2, v10
	v_or3_b32 v10, v19, v20, v21
	v_or3_b32 v11, v22, v23, v24
	ds_bpermute_b32 v19, v91, v4
	ds_bpermute_b32 v18, v91, v2
	v_mov_b32_e32 v21, 0
	v_readlane_b32 s0, v86, s4
	s_ashr_i32 s1, s0, 31
	s_lshl_b64 s[0:1], s[0:1], 10
	v_lshl_add_u64 v[50:51], v[66:67], 0, s[0:1]
	global_load_dwordx4 v[50:53], v[50:51], off
	s_add_i32 s5, s4, 1
	s_add_i32 s29, s4, 2
	s_add_i32 s30, s4, 3
	s_add_i32 s31, s4, 4
	s_add_i32 s33, s4, 5
	s_add_i32 s34, s4, 6
	s_add_i32 s35, s4, 7
	s_add_i32 s36, s4, 8
	s_add_i32 s37, s4, 9
	s_add_i32 s38, s4, 10
	s_add_i32 s39, s4, 11
	s_add_i32 s40, s4, 12
	s_add_i32 s41, s4, 13
	s_add_i32 s42, s4, 14
	s_add_i32 s43, s4, 15
	v_readlane_b32 s46, v86, s5
	v_readlane_b32 s48, v86, s29
	v_readlane_b32 s50, v86, s30
	v_readlane_b32 s52, v86, s31
	v_readlane_b32 s54, v86, s33
	v_readlane_b32 s56, v86, s34
	v_readlane_b32 s58, v86, s35
	v_readlane_b32 s60, v86, s36
	v_readlane_b32 s62, v86, s37
	v_readlane_b32 s64, v86, s38
	v_readlane_b32 s66, v86, s39
	v_readlane_b32 s68, v86, s40
	v_readlane_b32 s70, v86, s41
	v_readlane_b32 s72, v86, s42
	v_readlane_b32 s74, v86, s43
	s_ashr_i32 s47, s46, 31
	s_ashr_i32 s49, s48, 31
	s_ashr_i32 s51, s50, 31
	s_ashr_i32 s53, s52, 31
	s_ashr_i32 s55, s54, 31
	s_ashr_i32 s57, s56, 31
	s_ashr_i32 s59, s58, 31
	s_ashr_i32 s61, s60, 31
	s_ashr_i32 s63, s62, 31
	s_ashr_i32 s65, s64, 31
	s_ashr_i32 s67, s66, 31
	s_ashr_i32 s69, s68, 31
	s_ashr_i32 s71, s70, 31
	s_ashr_i32 s73, s72, 31
	s_ashr_i32 s75, s74, 31
	s_lshl_b64 s[0:1], s[46:47], 10
	s_lshl_b64 s[46:47], s[48:49], 10
; __device__ void peer_phase(const Params& p) {
;     ...
;       for (int e = 0; e < 64; e += 16) {
;         uint4 d[16];
; #pragma unroll
;         for (int u = 0; u < 16; ++u) {
;           const int id = __builtin_amdgcn_readlane(eid[hf], e + u);
;           d[u] = ((const uint4*)(down4 + (size_t)id * 1024))[lane];
;         }
; #pragma unroll
;         for (int u = 0; u < 16; ++u) {
;           const u32 w[4] = {d[u].x, d[u].y, d[u].z, d[u].w};
;           int s0 = 0, s1 = 0;
; #pragma unroll
;           for (int k = 0; k < 4; ++k) {
;             s0 = __builtin_amdgcn_sdot4((int)(w[k] & 0x0F0F0F0Fu), hq[2 * k], s0, false);
;             s1 = __builtin_amdgcn_sdot4((int)((w[k] >> 4) & 0x0F0F0F0Fu), hq[2 * k + 1], s1, false);
;           }
	s_lshl_b64 s[48:49], s[50:51], 10
	s_lshl_b64 s[50:51], s[52:53], 10
	s_lshl_b64 s[52:53], s[54:55], 10
	s_lshl_b64 s[54:55], s[56:57], 10
	s_lshl_b64 s[56:57], s[58:59], 10
	s_lshl_b64 s[58:59], s[60:61], 10
	s_lshl_b64 s[60:61], s[62:63], 10
	s_lshl_b64 s[62:63], s[64:65], 10
	s_lshl_b64 s[64:65], s[66:67], 10
	s_lshl_b64 s[66:67], s[68:69], 10
	s_lshl_b64 s[68:69], s[70:71], 10
	s_lshl_b64 s[70:71], s[72:73], 10
	s_lshl_b64 s[72:73], s[74:75], 10
	v_lshl_add_u64 v[54:55], v[66:67], 0, s[0:1]
	v_lshl_add_u64 v[58:59], v[66:67], 0, s[46:47]
	v_lshl_add_u64 v[108:109], v[66:67], 0, s[50:51]
	v_lshl_add_u64 v[112:113], v[66:67], 0, s[52:53]
	v_lshl_add_u64 v[116:117], v[66:67], 0, s[54:55]
	v_lshl_add_u64 v[120:121], v[66:67], 0, s[56:57]
	v_lshl_add_u64 v[124:125], v[66:67], 0, s[58:59]
	v_lshl_add_u64 v[128:129], v[66:67], 0, s[60:61]
	v_lshl_add_u64 v[132:133], v[66:67], 0, s[62:63]
	v_lshl_add_u64 v[136:137], v[66:67], 0, s[64:65]
	v_lshl_add_u64 v[140:141], v[66:67], 0, s[66:67]
	v_lshl_add_u64 v[144:145], v[66:67], 0, s[68:69]
	v_lshl_add_u64 v[148:149], v[66:67], 0, s[70:71]
	v_lshl_add_u64 v[152:153], v[66:67], 0, s[72:73]
	v_lshl_add_u64 v[62:63], v[66:67], 0, s[48:49]
	global_load_dwordx4 v[54:57], v[54:55], off
	s_nop 0
	global_load_dwordx4 v[58:61], v[58:59], off
	s_nop 0
	global_load_dwordx4 v[104:107], v[62:63], off
	s_nop 0
	global_load_dwordx4 v[108:111], v[108:109], off
	s_nop 0
	global_load_dwordx4 v[112:115], v[112:113], off
	s_nop 0
	global_load_dwordx4 v[116:119], v[116:117], off
	s_nop 0
	global_load_dwordx4 v[120:123], v[120:121], off
	s_nop 0
	global_load_dwordx4 v[124:127], v[124:125], off
	s_nop 0
	global_load_dwordx4 v[128:131], v[128:129], off
	s_nop 0
	global_load_dwordx4 v[132:135], v[132:133], off
	s_nop 0
	global_load_dwordx4 v[136:139], v[136:137], off
	s_nop 0
	global_load_dwordx4 v[140:143], v[140:141], off
	s_nop 0
	global_load_dwordx4 v[144:147], v[144:145], off
	s_nop 0
	global_load_dwordx4 v[148:151], v[148:149], off
	s_nop 0
	global_load_dwordx4 v[152:155], v[152:153], off
.LBB0_851:
	v_mov_b32_e32 v20, 0
	v_mov_b32_e32 v22, 0
	v_mov_b32_e32 v23, 0
	s_waitcnt vmcnt(15)
	v_and_b32_e32 v62, 0xf0f0f0f, v50
	v_lshrrev_b32_e32 v50, 4, v50
	v_and_b32_e32 v63, 0xf0f0f0f, v51
	v_lshrrev_b32_e32 v51, 4, v51
	v_dot4c_i32_i8_e32 v20, v62, v5
	v_and_b32_e32 v50, 0xf0f0f0f, v50
	v_mov_b32_e32 v24, 0
	v_and_b32_e32 v87, 0xf0f0f0f, v52
	v_lshrrev_b32_e32 v52, 4, v52
	v_and_b32_e32 v51, 0xf0f0f0f, v51
	v_dot4c_i32_i8_e32 v22, v50, v6
	v_mov_b32_e32 v25, 0
	v_mov_b32_e32 v26, 0
	v_mov_b32_e32 v29, 0
	v_mov_b32_e32 v30, 0
	v_mov_b32_e32 v37, 0
	v_mov_b32_e32 v38, 0
	v_and_b32_e32 v103, 0xf0f0f0f, v53
	v_lshrrev_b32_e32 v53, 4, v53
	v_and_b32_e32 v52, 0xf0f0f0f, v52
	v_dot4c_i32_i8_e32 v20, v63, v7
	v_dot4c_i32_i8_e32 v22, v51, v8
	v_mov_b32_e32 v27, 0
	v_mov_b32_e32 v28, 0
	v_mov_b32_e32 v31, 0
	v_mov_b32_e32 v32, 0
	v_mov_b32_e32 v39, 0
	v_mov_b32_e32 v40, 0
	v_and_b32_e32 v53, 0xf0f0f0f, v53
	v_dot4c_i32_i8_e32 v20, v87, v9
	v_dot4c_i32_i8_e32 v22, v52, v10
	v_dot4c_i32_i8_e32 v20, v103, v11
	v_dot4c_i32_i8_e32 v22, v53, v12
	v_mov_b32_e32 v41, 0
	v_mov_b32_e32 v42, 0
	v_mov_b32_e32 v33, 0
	v_add_u32_e32 v20, v22, v20
	v_mov_b32_e32 v34, 0
	v_mov_b32_e32 v35, 0
	v_mov_b32_e32 v36, 0
	v_mov_b32_e32 v43, 0
	v_mov_b32_e32 v44, 0
	v_mov_b32_e32 v45, 0
	v_mov_b32_e32 v46, 0
	v_mov_b32_e32 v47, 0
	v_mov_b32_e32 v48, 0
	v_mov_b32_e32 v49, 0
	v_mov_b32_e32 v77, 0
	v_mov_b32_e32 v79, 0
	v_mov_b32_e32 v83, 0
	s_waitcnt vmcnt(14)
	v_and_b32_e32 v62, 0xf0f0f0f, v54
	v_lshrrev_b32_e32 v54, 4, v54
	v_and_b32_e32 v156, 0xf0f0f0f, v55
	v_lshrrev_b32_e32 v55, 4, v55
	v_and_b32_e32 v157, 0xf0f0f0f, v56
	v_lshrrev_b32_e32 v56, 4, v56
	v_and_b32_e32 v158, 0xf0f0f0f, v57
	v_lshrrev_b32_e32 v57, 4, v57
	s_waitcnt vmcnt(13)
	v_and_b32_e32 v159, 0xf0f0f0f, v58
	v_lshrrev_b32_e32 v58, 4, v58
	s_waitcnt vmcnt(12)
	v_and_b32_e32 v164, 0xf0f0f0f, v105
	v_lshrrev_b32_e32 v105, 4, v105
	v_and_b32_e32 v165, 0xf0f0f0f, v106
	v_lshrrev_b32_e32 v106, 4, v106
	s_waitcnt vmcnt(11)
	v_and_b32_e32 v167, 0xf0f0f0f, v108
	v_lshrrev_b32_e32 v108, 4, v108
	v_and_b32_e32 v168, 0xf0f0f0f, v109
	v_lshrrev_b32_e32 v109, 4, v109
	s_waitcnt vmcnt(10)
	v_and_b32_e32 v171, 0xf0f0f0f, v112
	v_lshrrev_b32_e32 v112, 4, v112
	v_and_b32_e32 v174, 0xf0f0f0f, v115
	v_lshrrev_b32_e32 v115, 4, v115
	s_waitcnt vmcnt(9)
	v_and_b32_e32 v177, 0xf0f0f0f, v118
	v_lshrrev_b32_e32 v118, 4, v118
	s_waitcnt vmcnt(8)
	v_and_b32_e32 v180, 0xf0f0f0f, v121
	v_lshrrev_b32_e32 v121, 4, v121
	s_waitcnt vmcnt(7)
	v_and_b32_e32 v183, 0xf0f0f0f, v124
	v_lshrrev_b32_e32 v124, 4, v124
	v_and_b32_e32 v50, 0xf0f0f0f, v54
	v_and_b32_e32 v160, 0xf0f0f0f, v59
	v_lshrrev_b32_e32 v59, 4, v59
	v_and_b32_e32 v161, 0xf0f0f0f, v60
	v_lshrrev_b32_e32 v60, 4, v60
	v_and_b32_e32 v162, 0xf0f0f0f, v61
	v_lshrrev_b32_e32 v61, 4, v61
	v_and_b32_e32 v163, 0xf0f0f0f, v104
	v_lshrrev_b32_e32 v104, 4, v104
	v_and_b32_e32 v166, 0xf0f0f0f, v107
	v_lshrrev_b32_e32 v107, 4, v107
	v_and_b32_e32 v169, 0xf0f0f0f, v110
	v_lshrrev_b32_e32 v110, 4, v110
	v_and_b32_e32 v172, 0xf0f0f0f, v113
	v_lshrrev_b32_e32 v113, 4, v113
	v_and_b32_e32 v175, 0xf0f0f0f, v116
	v_lshrrev_b32_e32 v116, 4, v116
	v_and_b32_e32 v178, 0xf0f0f0f, v119
	v_lshrrev_b32_e32 v119, 4, v119
	v_and_b32_e32 v181, 0xf0f0f0f, v122
	v_lshrrev_b32_e32 v122, 4, v122
	v_and_b32_e32 v184, 0xf0f0f0f, v125
	v_lshrrev_b32_e32 v125, 4, v125
	s_waitcnt vmcnt(6)
; __device__ void peer_phase(const Params& p) {
;     ...
;         for (int u = 0; u < 16; ++u) {
;           const u32 w[4] = {d[u].x, d[u].y, d[u].z, d[u].w};
;           int s0 = 0, s1 = 0;
; #pragma unroll
;           for (int k = 0; k < 4; ++k) {
;             s0 = __builtin_amdgcn_sdot4((int)(w[k] & 0x0F0F0F0Fu), hq[2 * k], s0, false);
;             s1 = __builtin_amdgcn_sdot4((int)((w[k] >> 4) & 0x0F0F0F0Fu), hq[2 * k + 1], s1, false);
;           }
	v_and_b32_e32 v187, 0xf0f0f0f, v128
	v_lshrrev_b32_e32 v128, 4, v128
	v_dot4c_i32_i8_e32 v23, v62, v5
	v_and_b32_e32 v54, 0xf0f0f0f, v55
	v_and_b32_e32 v55, 0xf0f0f0f, v56
	v_and_b32_e32 v56, 0xf0f0f0f, v57
	v_and_b32_e32 v57, 0xf0f0f0f, v58
	v_and_b32_e32 v62, 0xf0f0f0f, v105
	v_and_b32_e32 v63, 0xf0f0f0f, v106
	v_and_b32_e32 v105, 0xf0f0f0f, v108
	v_and_b32_e32 v106, 0xf0f0f0f, v109
	v_and_b32_e32 v109, 0xf0f0f0f, v112
	v_and_b32_e32 v112, 0xf0f0f0f, v115
	v_and_b32_e32 v115, 0xf0f0f0f, v118
	v_and_b32_e32 v118, 0xf0f0f0f, v121
	v_and_b32_e32 v121, 0xf0f0f0f, v124
	v_dot4c_i32_i8_e32 v24, v50, v6
	v_and_b32_e32 v170, 0xf0f0f0f, v111
	v_lshrrev_b32_e32 v111, 4, v111
	v_and_b32_e32 v173, 0xf0f0f0f, v114
	v_lshrrev_b32_e32 v114, 4, v114
	v_and_b32_e32 v176, 0xf0f0f0f, v117
	v_lshrrev_b32_e32 v117, 4, v117
	v_and_b32_e32 v179, 0xf0f0f0f, v120
	v_lshrrev_b32_e32 v120, 4, v120
	v_and_b32_e32 v182, 0xf0f0f0f, v123
	v_lshrrev_b32_e32 v123, 4, v123
	v_and_b32_e32 v185, 0xf0f0f0f, v126
	v_lshrrev_b32_e32 v126, 4, v126
	v_and_b32_e32 v188, 0xf0f0f0f, v129
	v_lshrrev_b32_e32 v129, 4, v129
	v_dot4c_i32_i8_e32 v25, v159, v5
	v_and_b32_e32 v58, 0xf0f0f0f, v59
	v_and_b32_e32 v59, 0xf0f0f0f, v60
	v_and_b32_e32 v60, 0xf0f0f0f, v61
	v_and_b32_e32 v61, 0xf0f0f0f, v104
	v_and_b32_e32 v104, 0xf0f0f0f, v107
	v_dot4c_i32_i8_e32 v29, v167, v5
	v_and_b32_e32 v107, 0xf0f0f0f, v110
	v_and_b32_e32 v110, 0xf0f0f0f, v113
	v_and_b32_e32 v113, 0xf0f0f0f, v116
	v_and_b32_e32 v116, 0xf0f0f0f, v119
	v_and_b32_e32 v119, 0xf0f0f0f, v122
	v_dot4c_i32_i8_e32 v37, v183, v5
	v_and_b32_e32 v122, 0xf0f0f0f, v125
	v_and_b32_e32 v125, 0xf0f0f0f, v128
	v_dot4c_i32_i8_e32 v23, v156, v7
	v_dot4c_i32_i8_e32 v26, v57, v6
	v_dot4c_i32_i8_e32 v30, v105, v6
	v_dot4c_i32_i8_e32 v38, v121, v6
	v_dot4c_i32_i8_e32 v24, v54, v8
	v_and_b32_e32 v186, 0xf0f0f0f, v127
	v_lshrrev_b32_e32 v127, 4, v127
	v_and_b32_e32 v189, 0xf0f0f0f, v130
	v_lshrrev_b32_e32 v130, 4, v130
	s_waitcnt vmcnt(5)
	v_and_b32_e32 v191, 0xf0f0f0f, v132
	v_lshrrev_b32_e32 v132, 4, v132
	v_dot4c_i32_i8_e32 v27, v163, v5
	v_and_b32_e32 v108, 0xf0f0f0f, v111
	v_dot4c_i32_i8_e32 v31, v171, v5
	v_and_b32_e32 v111, 0xf0f0f0f, v114
	v_and_b32_e32 v114, 0xf0f0f0f, v117
	v_and_b32_e32 v117, 0xf0f0f0f, v120
	v_and_b32_e32 v120, 0xf0f0f0f, v123
	v_and_b32_e32 v123, 0xf0f0f0f, v126
	v_dot4c_i32_i8_e32 v39, v187, v5
	v_and_b32_e32 v126, 0xf0f0f0f, v129
	v_dot4c_i32_i8_e32 v25, v160, v7
	v_dot4c_i32_i8_e32 v28, v61, v6
	v_dot4c_i32_i8_e32 v29, v168, v7
	v_dot4c_i32_i8_e32 v32, v109, v6
	v_dot4c_i32_i8_e32 v37, v184, v7
	v_dot4c_i32_i8_e32 v40, v125, v6
	v_dot4c_i32_i8_e32 v23, v157, v9
	v_dot4c_i32_i8_e32 v26, v58, v8
	v_dot4c_i32_i8_e32 v30, v106, v8
	v_dot4c_i32_i8_e32 v38, v122, v8
	v_dot4c_i32_i8_e32 v24, v55, v10
	v_and_b32_e32 v190, 0xf0f0f0f, v131
	v_lshrrev_b32_e32 v131, 4, v131
	v_and_b32_e32 v192, 0xf0f0f0f, v133
	v_lshrrev_b32_e32 v133, 4, v133
	v_and_b32_e32 v124, 0xf0f0f0f, v127
	v_and_b32_e32 v127, 0xf0f0f0f, v130
	v_and_b32_e32 v129, 0xf0f0f0f, v132
	v_dot4c_i32_i8_e32 v27, v164, v7
	v_dot4c_i32_i8_e32 v31, v172, v7
	v_dot4c_i32_i8_e32 v39, v188, v7
	v_dot4c_i32_i8_e32 v25, v161, v9
	v_dot4c_i32_i8_e32 v28, v62, v8
	v_dot4c_i32_i8_e32 v29, v169, v9
	v_dot4c_i32_i8_e32 v32, v110, v8
	v_dot4c_i32_i8_e32 v37, v185, v9
	v_dot4c_i32_i8_e32 v40, v126, v8
	v_dot4c_i32_i8_e32 v23, v158, v11
	v_dot4c_i32_i8_e32 v26, v59, v10
	v_dot4c_i32_i8_e32 v30, v107, v10
	v_dot4c_i32_i8_e32 v38, v123, v10
	v_dot4c_i32_i8_e32 v24, v56, v12
	v_and_b32_e32 v193, 0xf0f0f0f, v134
	v_lshrrev_b32_e32 v134, 4, v134
	s_waitcnt vmcnt(4)
	v_and_b32_e32 v195, 0xf0f0f0f, v136
	v_lshrrev_b32_e32 v136, 4, v136
	v_and_b32_e32 v128, 0xf0f0f0f, v131
	v_dot4c_i32_i8_e32 v41, v191, v5
	v_and_b32_e32 v130, 0xf0f0f0f, v133
	v_dot4c_i32_i8_e32 v42, v129, v6
	v_dot4c_i32_i8_e32 v27, v165, v9
	v_dot4c_i32_i8_e32 v31, v173, v9
	v_dot4c_i32_i8_e32 v39, v189, v9
	v_dot4c_i32_i8_e32 v25, v162, v11
	v_dot4c_i32_i8_e32 v28, v63, v10
	v_dot4c_i32_i8_e32 v29, v170, v11
	v_dot4c_i32_i8_e32 v32, v111, v10
	v_dot4c_i32_i8_e32 v37, v186, v11
	v_dot4c_i32_i8_e32 v40, v127, v10
	v_dot4c_i32_i8_e32 v26, v60, v12
	v_dot4c_i32_i8_e32 v30, v108, v12
	v_dot4c_i32_i8_e32 v38, v124, v12
	v_add_u32_e32 v23, v24, v23
	v_and_b32_e32 v194, 0xf0f0f0f, v135
	v_lshrrev_b32_e32 v135, 4, v135
	v_and_b32_e32 v196, 0xf0f0f0f, v137
	v_lshrrev_b32_e32 v137, 4, v137
	v_dot4c_i32_i8_e32 v33, v175, v5
	v_and_b32_e32 v131, 0xf0f0f0f, v134
	v_and_b32_e32 v133, 0xf0f0f0f, v136
	v_dot4c_i32_i8_e32 v34, v113, v6
	v_dot4c_i32_i8_e32 v41, v192, v7
	v_dot4c_i32_i8_e32 v42, v130, v8
	v_dot4c_i32_i8_e32 v27, v166, v11
	v_dot4c_i32_i8_e32 v31, v174, v11
	v_dot4c_i32_i8_e32 v39, v190, v11
	v_dot4c_i32_i8_e32 v28, v104, v12
	v_dot4c_i32_i8_e32 v32, v112, v12
	v_dot4c_i32_i8_e32 v40, v128, v12
	v_add_u32_e32 v24, v26, v25
	v_add_u32_e32 v26, v30, v29
	v_add_u32_e32 v30, v38, v37
	v_and_b32_e32 v197, 0xf0f0f0f, v138
	v_lshrrev_b32_e32 v138, 4, v138
	s_waitcnt vmcnt(3)
	v_and_b32_e32 v199, 0xf0f0f0f, v140
	v_lshrrev_b32_e32 v140, 4, v140
	v_dot4c_i32_i8_e32 v35, v179, v5
	v_and_b32_e32 v132, 0xf0f0f0f, v135
	v_dot4c_i32_i8_e32 v43, v195, v5
	v_and_b32_e32 v134, 0xf0f0f0f, v137
	v_dot4c_i32_i8_e32 v33, v176, v7
	v_dot4c_i32_i8_e32 v36, v117, v6
	v_dot4c_i32_i8_e32 v44, v133, v6
	v_dot4c_i32_i8_e32 v34, v114, v8
	v_dot4c_i32_i8_e32 v41, v193, v9
	v_dot4c_i32_i8_e32 v42, v131, v10
	v_add_u32_e32 v25, v28, v27
	v_add_u32_e32 v27, v32, v31
	v_add_u32_e32 v31, v40, v39
	v_and_b32_e32 v198, 0xf0f0f0f, v139
	v_lshrrev_b32_e32 v139, 4, v139
	v_and_b32_e32 v200, 0xf0f0f0f, v141
	v_lshrrev_b32_e32 v141, 4, v141
	v_and_b32_e32 v135, 0xf0f0f0f, v138
	v_and_b32_e32 v137, 0xf0f0f0f, v140
	v_dot4c_i32_i8_e32 v35, v180, v7
	v_dot4c_i32_i8_e32 v43, v196, v7
	v_dot4c_i32_i8_e32 v33, v177, v9
	v_dot4c_i32_i8_e32 v36, v118, v8
	v_dot4c_i32_i8_e32 v44, v134, v8
	v_dot4c_i32_i8_e32 v34, v115, v10
	v_dot4c_i32_i8_e32 v41, v194, v11
	v_dot4c_i32_i8_e32 v42, v132, v12
	v_and_b32_e32 v201, 0xf0f0f0f, v142
	v_lshrrev_b32_e32 v142, 4, v142
	s_waitcnt vmcnt(2)
; __device__ void peer_phase(const Params& p) {
;     ...
;       for (int e = 0; e < 64; e += 16) {
;         uint4 d[16];
; #pragma unroll
;         for (int u = 0; u < 16; ++u) {
;           const int id = __builtin_amdgcn_readlane(eid[hf], e + u);
;           d[u] = ((const uint4*)(down4 + (size_t)id * 1024))[lane];
;         }
; #pragma unroll
;         for (int u = 0; u < 16; ++u) {
;           const u32 w[4] = {d[u].x, d[u].y, d[u].z, d[u].w};
;           int s0 = 0, s1 = 0;
; #pragma unroll
;           for (int k = 0; k < 4; ++k) {
;             s0 = __builtin_amdgcn_sdot4((int)(w[k] & 0x0F0F0F0Fu), hq[2 * k], s0, false);
;             s1 = __builtin_amdgcn_sdot4((int)((w[k] >> 4) & 0x0F0F0F0Fu), hq[2 * k + 1], s1, false);
;           }
;           const int sI = wave_sum_i(s0 + s1);
;           if (lane == e + u) acti = sI;
	v_and_b32_e32 v203, 0xf0f0f0f, v144
	v_lshrrev_b32_e32 v144, 4, v144
	v_and_b32_e32 v136, 0xf0f0f0f, v139
	v_dot4c_i32_i8_e32 v45, v199, v5
	v_and_b32_e32 v138, 0xf0f0f0f, v141
	v_dot4c_i32_i8_e32 v46, v137, v6
	v_dot4c_i32_i8_e32 v35, v181, v9
	v_dot4c_i32_i8_e32 v43, v197, v9
	v_dot4c_i32_i8_e32 v33, v178, v11
	v_dot4c_i32_i8_e32 v36, v119, v10
	v_dot4c_i32_i8_e32 v44, v135, v10
	v_dot4c_i32_i8_e32 v34, v116, v12
	v_add_u32_e32 v32, v42, v41
	v_and_b32_e32 v202, 0xf0f0f0f, v143
	v_lshrrev_b32_e32 v143, 4, v143
	v_and_b32_e32 v204, 0xf0f0f0f, v145
	v_lshrrev_b32_e32 v145, 4, v145
	v_and_b32_e32 v139, 0xf0f0f0f, v142
	v_and_b32_e32 v141, 0xf0f0f0f, v144
	v_dot4c_i32_i8_e32 v45, v200, v7
	v_dot4c_i32_i8_e32 v46, v138, v8
	v_dot4c_i32_i8_e32 v35, v182, v11
	v_dot4c_i32_i8_e32 v43, v198, v11
	v_dot4c_i32_i8_e32 v36, v120, v12
	v_dot4c_i32_i8_e32 v44, v136, v12
	v_add_u32_e32 v28, v34, v33
	v_and_b32_e32 v205, 0xf0f0f0f, v146
	v_lshrrev_b32_e32 v146, 4, v146
	s_waitcnt vmcnt(1)
	v_and_b32_e32 v207, 0xf0f0f0f, v148
	v_lshrrev_b32_e32 v148, 4, v148
	v_and_b32_e32 v140, 0xf0f0f0f, v143
	v_dot4c_i32_i8_e32 v47, v203, v5
	v_and_b32_e32 v142, 0xf0f0f0f, v145
	v_dot4c_i32_i8_e32 v48, v141, v6
	v_dot4c_i32_i8_e32 v45, v201, v9
	v_dot4c_i32_i8_e32 v46, v139, v10
	v_add_u32_e32 v29, v36, v35
	v_add_u32_e32 v33, v44, v43
	v_and_b32_e32 v206, 0xf0f0f0f, v147
	v_lshrrev_b32_e32 v147, 4, v147
	v_and_b32_e32 v208, 0xf0f0f0f, v149
	v_lshrrev_b32_e32 v149, 4, v149
	v_and_b32_e32 v143, 0xf0f0f0f, v146
	v_and_b32_e32 v145, 0xf0f0f0f, v148
	v_dot4c_i32_i8_e32 v47, v204, v7
	v_dot4c_i32_i8_e32 v48, v142, v8
	v_dot4c_i32_i8_e32 v45, v202, v11
	v_dot4c_i32_i8_e32 v46, v140, v12
	v_and_b32_e32 v209, 0xf0f0f0f, v150
	v_lshrrev_b32_e32 v150, 4, v150
	s_waitcnt vmcnt(0)
	v_and_b32_e32 v211, 0xf0f0f0f, v152
	v_lshrrev_b32_e32 v152, 4, v152
	v_and_b32_e32 v144, 0xf0f0f0f, v147
	v_dot4c_i32_i8_e32 v49, v207, v5
	v_and_b32_e32 v146, 0xf0f0f0f, v149
	v_dot4c_i32_i8_e32 v77, v145, v6
	v_dot4c_i32_i8_e32 v47, v205, v9
	v_dot4c_i32_i8_e32 v48, v143, v10
	v_add_u32_e32 v34, v46, v45
	v_and_b32_e32 v210, 0xf0f0f0f, v151
	v_lshrrev_b32_e32 v151, 4, v151
	v_and_b32_e32 v212, 0xf0f0f0f, v153
	v_lshrrev_b32_e32 v153, 4, v153
	v_and_b32_e32 v147, 0xf0f0f0f, v150
	v_and_b32_e32 v149, 0xf0f0f0f, v152
	v_dot4c_i32_i8_e32 v49, v208, v7
	v_dot4c_i32_i8_e32 v77, v146, v8
	v_dot4c_i32_i8_e32 v47, v206, v11
	v_dot4c_i32_i8_e32 v48, v144, v12
	v_and_b32_e32 v213, 0xf0f0f0f, v154
	v_lshrrev_b32_e32 v154, 4, v154
	v_and_b32_e32 v148, 0xf0f0f0f, v151
	v_dot4c_i32_i8_e32 v79, v211, v5
	v_and_b32_e32 v150, 0xf0f0f0f, v153
	v_dot4c_i32_i8_e32 v83, v149, v6
	v_dot4c_i32_i8_e32 v49, v209, v9
	v_dot4c_i32_i8_e32 v77, v147, v10
	v_add_u32_e32 v35, v48, v47
	v_and_b32_e32 v214, 0xf0f0f0f, v155
	v_lshrrev_b32_e32 v155, 4, v155
	v_and_b32_e32 v151, 0xf0f0f0f, v154
	v_dot4c_i32_i8_e32 v79, v212, v7
	v_dot4c_i32_i8_e32 v83, v150, v8
	v_dot4c_i32_i8_e32 v49, v210, v11
	v_dot4c_i32_i8_e32 v77, v148, v12
	v_and_b32_e32 v152, 0xf0f0f0f, v155
	v_dot4c_i32_i8_e32 v79, v213, v9
	v_dot4c_i32_i8_e32 v83, v151, v10
	v_add_u32_e32 v36, v77, v49
	v_dot4c_i32_i8_e32 v79, v214, v11
	v_dot4c_i32_i8_e32 v83, v152, v12
	s_nop 2
	v_add_u32_e32 v37, v83, v79
	s_add_i32 s4, s4, 16
	s_cmp_gt_u32 s4, 63
	s_cbranch_scc1 .Lp9_dskip1
	s_nop 3
	v_readlane_b32 s0, v86, s4
	s_ashr_i32 s1, s0, 31
	s_lshl_b64 s[0:1], s[0:1], 10
	v_lshl_add_u64 v[50:51], v[66:67], 0, s[0:1]
	global_load_dwordx4 v[50:53], v[50:51], off
	s_add_i32 s5, s4, 1
	s_add_i32 s29, s4, 2
	s_add_i32 s30, s4, 3
	s_add_i32 s31, s4, 4
	s_add_i32 s33, s4, 5
	s_add_i32 s34, s4, 6
	s_add_i32 s35, s4, 7
	s_add_i32 s36, s4, 8
	s_add_i32 s37, s4, 9
	s_add_i32 s38, s4, 10
	s_add_i32 s39, s4, 11
	s_add_i32 s40, s4, 12
	s_add_i32 s41, s4, 13
	s_add_i32 s42, s4, 14
	s_add_i32 s43, s4, 15
	v_readlane_b32 s46, v86, s5
	v_readlane_b32 s48, v86, s29
	v_readlane_b32 s50, v86, s30
	v_readlane_b32 s52, v86, s31
	v_readlane_b32 s54, v86, s33
	v_readlane_b32 s56, v86, s34
	v_readlane_b32 s58, v86, s35
	v_readlane_b32 s60, v86, s36
	v_readlane_b32 s62, v86, s37
	v_readlane_b32 s64, v86, s38
	v_readlane_b32 s66, v86, s39
	v_readlane_b32 s68, v86, s40
	v_readlane_b32 s70, v86, s41
	v_readlane_b32 s72, v86, s42
	v_readlane_b32 s74, v86, s43
	s_ashr_i32 s47, s46, 31
	s_ashr_i32 s49, s48, 31
	s_ashr_i32 s51, s50, 31
	s_ashr_i32 s53, s52, 31
	s_ashr_i32 s55, s54, 31
	s_ashr_i32 s57, s56, 31
	s_ashr_i32 s59, s58, 31
	s_ashr_i32 s61, s60, 31
	s_ashr_i32 s63, s62, 31
	s_ashr_i32 s65, s64, 31
	s_ashr_i32 s67, s66, 31
	s_ashr_i32 s69, s68, 31
	s_ashr_i32 s71, s70, 31
	s_ashr_i32 s73, s72, 31
	s_ashr_i32 s75, s74, 31
	s_lshl_b64 s[0:1], s[46:47], 10
	s_lshl_b64 s[46:47], s[48:49], 10
	s_lshl_b64 s[48:49], s[50:51], 10
	s_lshl_b64 s[50:51], s[52:53], 10
	s_lshl_b64 s[52:53], s[54:55], 10
	s_lshl_b64 s[54:55], s[56:57], 10
	s_lshl_b64 s[56:57], s[58:59], 10
	s_lshl_b64 s[58:59], s[60:61], 10
	s_lshl_b64 s[60:61], s[62:63], 10
	s_lshl_b64 s[62:63], s[64:65], 10
	s_lshl_b64 s[64:65], s[66:67], 10
	s_lshl_b64 s[66:67], s[68:69], 10
	s_lshl_b64 s[68:69], s[70:71], 10
	s_lshl_b64 s[70:71], s[72:73], 10
	s_lshl_b64 s[72:73], s[74:75], 10
	v_lshl_add_u64 v[54:55], v[66:67], 0, s[0:1]
	v_lshl_add_u64 v[58:59], v[66:67], 0, s[46:47]
	v_lshl_add_u64 v[108:109], v[66:67], 0, s[50:51]
	v_lshl_add_u64 v[112:113], v[66:67], 0, s[52:53]
	v_lshl_add_u64 v[116:117], v[66:67], 0, s[54:55]
	v_lshl_add_u64 v[120:121], v[66:67], 0, s[56:57]
	v_lshl_add_u64 v[124:125], v[66:67], 0, s[58:59]
	v_lshl_add_u64 v[128:129], v[66:67], 0, s[60:61]
	v_lshl_add_u64 v[132:133], v[66:67], 0, s[62:63]
	v_lshl_add_u64 v[136:137], v[66:67], 0, s[64:65]
	v_lshl_add_u64 v[140:141], v[66:67], 0, s[66:67]
	v_lshl_add_u64 v[144:145], v[66:67], 0, s[68:69]
	v_lshl_add_u64 v[148:149], v[66:67], 0, s[70:71]
	v_lshl_add_u64 v[152:153], v[66:67], 0, s[72:73]
	v_lshl_add_u64 v[62:63], v[66:67], 0, s[48:49]
	global_load_dwordx4 v[54:57], v[54:55], off
	s_nop 0
	global_load_dwordx4 v[58:61], v[58:59], off
	s_nop 0
	global_load_dwordx4 v[104:107], v[62:63], off
	s_nop 0
	global_load_dwordx4 v[108:111], v[108:109], off
	s_nop 0
	global_load_dwordx4 v[112:115], v[112:113], off
	s_nop 0
	global_load_dwordx4 v[116:119], v[116:117], off
	s_nop 0
	global_load_dwordx4 v[120:123], v[120:121], off
	s_nop 0
	global_load_dwordx4 v[124:127], v[124:125], off
	s_nop 0
	global_load_dwordx4 v[128:131], v[128:129], off
	s_nop 0
	global_load_dwordx4 v[132:135], v[132:133], off
	s_nop 0
	global_load_dwordx4 v[136:139], v[136:137], off
	s_nop 0
	global_load_dwordx4 v[140:143], v[140:141], off
	s_nop 0
	global_load_dwordx4 v[144:147], v[144:145], off
	s_nop 0
	global_load_dwordx4 v[148:151], v[148:149], off
	s_nop 0
	global_load_dwordx4 v[152:155], v[152:153], off
; __device__ void peer_phase(const Params& p) {
;     ...
;           const int sI = wave_sum_i(s0 + s1);
;           if (lane == e + u) acti = sI;
;         }
;       }
;       const float act = ((float)acti - 7.5f * (float)hsum) * sh * (hf == 0 ? ds0 : ds1);
;       gg[hf] *= 0.5f * act * (1.f + erff(act * 0.70710678118654752f)) * (hf == 0 ? us0 : us1);
.Lp9_dskip1:
	s_add_i32 s44, s4, -16
	s_cmp_gt_u32 s44, 47
	s_nop 1
	v_add_u32_dpp v38, v20, v20 row_mirror row_mask:0xf bank_mask:0x3
	v_add_u32_dpp v38, v30, v30 row_mirror row_mask:0xf bank_mask:0xc
	v_add_u32_dpp v39, v23, v23 row_mirror row_mask:0xf bank_mask:0x3
	v_add_u32_dpp v39, v31, v31 row_mirror row_mask:0xf bank_mask:0xc
	v_add_u32_dpp v40, v24, v24 row_mirror row_mask:0xf bank_mask:0x3
	v_add_u32_dpp v40, v32, v32 row_mirror row_mask:0xf bank_mask:0xc
	v_add_u32_dpp v41, v25, v25 row_mirror row_mask:0xf bank_mask:0x3
	v_add_u32_dpp v41, v33, v33 row_mirror row_mask:0xf bank_mask:0xc
	v_add_u32_dpp v42, v26, v26 row_mirror row_mask:0xf bank_mask:0x3
	v_add_u32_dpp v42, v34, v34 row_mirror row_mask:0xf bank_mask:0xc
	v_add_u32_dpp v43, v27, v27 row_mirror row_mask:0xf bank_mask:0x3
	v_add_u32_dpp v43, v35, v35 row_mirror row_mask:0xf bank_mask:0xc
	v_add_u32_dpp v44, v28, v28 row_mirror row_mask:0xf bank_mask:0x3
	v_add_u32_dpp v44, v36, v36 row_mirror row_mask:0xf bank_mask:0xc
	v_add_u32_dpp v45, v29, v29 row_mirror row_mask:0xf bank_mask:0x3
	v_add_u32_dpp v45, v37, v37 row_mirror row_mask:0xf bank_mask:0xc
	v_add_u32_dpp v46, v38, v38 row_half_mirror row_mask:0xf bank_mask:0x5
	v_add_u32_dpp v46, v42, v42 row_half_mirror row_mask:0xf bank_mask:0xa
	v_add_u32_dpp v47, v39, v39 row_half_mirror row_mask:0xf bank_mask:0x5
	v_add_u32_dpp v47, v43, v43 row_half_mirror row_mask:0xf bank_mask:0xa
	v_add_u32_dpp v48, v40, v40 row_half_mirror row_mask:0xf bank_mask:0x5
	v_add_u32_dpp v48, v44, v44 row_half_mirror row_mask:0xf bank_mask:0xa
	v_add_u32_dpp v49, v41, v41 row_half_mirror row_mask:0xf bank_mask:0x5
	v_add_u32_dpp v49, v45, v45 row_half_mirror row_mask:0xf bank_mask:0xa
	v_add_u32_dpp v46, v46, v46 quad_perm:[1,0,3,2] row_mask:0xf bank_mask:0xf
	v_add_u32_dpp v47, v47, v47 quad_perm:[1,0,3,2] row_mask:0xf bank_mask:0xf
	v_add_u32_dpp v48, v48, v48 quad_perm:[1,0,3,2] row_mask:0xf bank_mask:0xf
	v_add_u32_dpp v49, v49, v49 quad_perm:[1,0,3,2] row_mask:0xf bank_mask:0xf
	v_add_u32_dpp v46, v46, v46 quad_perm:[2,3,0,1] row_mask:0xf bank_mask:0xf
	v_add_u32_dpp v47, v47, v47 quad_perm:[2,3,0,1] row_mask:0xf bank_mask:0xf
	v_add_u32_dpp v48, v48, v48 quad_perm:[2,3,0,1] row_mask:0xf bank_mask:0xf
	v_add_u32_dpp v49, v49, v49 quad_perm:[2,3,0,1] row_mask:0xf bank_mask:0xf
	s_mov_b32 vcc_lo, 0x22222222
	s_mov_b32 vcc_hi, 0x22222222
	s_nop 1
	v_cndmask_b32_e32 v46, v46, v47, vcc
	s_mov_b32 vcc_lo, 0x44444444
	s_mov_b32 vcc_hi, 0x44444444
	s_nop 1
	v_cndmask_b32_e32 v46, v46, v48, vcc
	s_mov_b32 vcc_lo, 0x88888888
	s_mov_b32 vcc_hi, 0x88888888
	s_nop 1
	v_cndmask_b32_e32 v46, v46, v49, vcc
	ds_bpermute_b32 v22, v90, v46
	v_and_b32_e32 v47, 48, v88
	v_cmp_eq_u32_e32 vcc, s44, v47
	s_waitcnt lgkmcnt(0)
	v_add_u32_e32 v46, v22, v46
	ds_bpermute_b32 v22, v89, v46
	s_waitcnt lgkmcnt(0)
	v_add_u32_e32 v46, v22, v46
	s_nop 1
	v_cndmask_b32_e32 v21, v21, v46, vcc
	s_cbranch_scc0 .LBB0_851
	v_add_f32_e32 v19, v4, v19
	ds_bpermute_b32 v20, v92, v19
	v_add_f32_e32 v18, v2, v18
	ds_bpermute_b32 v22, v92, v18
	v_add_u32_e32 v14, v14, v15
	v_mul_f32_e32 v13, 0x3c010204, v13
	s_waitcnt lgkmcnt(1)
	v_add_f32_e32 v15, v19, v20
	ds_bpermute_b32 v19, v93, v15
	s_waitcnt lgkmcnt(1)
	v_add_f32_e32 v18, v18, v22
	ds_bpermute_b32 v23, v93, v18
	v_mul_f32_e32 v20, v13, v17
	v_cvt_f32_i32_e32 v22, v14
	s_waitcnt lgkmcnt(1)
	v_add_f32_e32 v17, v15, v19
	v_cvt_f32_i32_e32 v15, v21
	s_waitcnt lgkmcnt(0)
	v_add_f32_e32 v13, v18, v23
	ds_bpermute_b32 v18, v94, v17
	ds_bpermute_b32 v14, v94, v13
	v_fmac_f32_e32 v15, 0xc0f00000, v22
	v_mul_f32_e32 v15, v20, v15
	v_mul_f32_e32 v15, v16, v15
	v_mul_f32_e32 v16, 0x3f3504f3, v15
	v_cmp_nlt_f32_e64 s[0:1], |v16|, 1.0
	s_and_saveexec_b64 s[4:5], s[0:1]
	s_xor_b64 s[0:1], exec, s[4:5]
	s_cbranch_execz .LBB0_854
	v_fma_f32 v19, |v16|, s12, v100
	v_fma_f32 v19, |v16|, v19, s13
	v_fma_f32 v19, |v16|, v19, s14
	v_fma_f32 v19, |v16|, v19, s15
	v_fma_f32 v19, |v16|, v19, s16
	v_fma_f32 v19, |v16|, v19, s17
	v_fma_f32 v19, |v16|, v19, |v16|
	v_mul_f32_e32 v21, 0xbfb8aa3b, v19
	v_fma_f32 v23, v19, s18, -v21
	v_rndne_f32_e32 v24, v21
	v_fmac_f32_e32 v23, 0xb2a5705f, v19
	v_sub_f32_e32 v21, v21, v24
	v_add_f32_e32 v21, v21, v23
	v_cvt_i32_f32_e32 v23, v24
	v_exp_f32_e32 v21, v21
	v_cmp_nlt_f32_e32 vcc, s19, v19
	v_ldexp_f32 v21, v21, v23
	s_nop 0
	v_cndmask_b32_e32 v21, 0, v21, vcc
	v_cmp_ngt_f32_e32 vcc, s20, v19
	s_nop 1
	v_cndmask_b32_e32 v19, v101, v21, vcc
	v_sub_f32_e32 v19, 1.0, v19
; __device__ void peer_phase(const Params& p) {
;     ...
;     for (int hf = 0; hf < 2; ++hf) {
;       int acti = 0;
;       for (int e = 0; e < 64; e += 16) {
;         uint4 d[16];
; #pragma unroll
;         for (int u = 0; u < 16; ++u) {
;           const int id = __builtin_amdgcn_readlane(eid[hf], e + u);
;           d[u] = ((const uint4*)(down4 + (size_t)id * 1024))[lane];
;         }
; #pragma unroll
;         for (int u = 0; u < 16; ++u) {
;           const u32 w[4] = {d[u].x, d[u].y, d[u].z, d[u].w};
;           int s0 = 0, s1 = 0;
; #pragma unroll
;           for (int k = 0; k < 4; ++k) {
;             s0 = __builtin_amdgcn_sdot4((int)(w[k] & 0x0F0F0F0Fu), hq[2 * k], s0, false);
;             s1 = __builtin_amdgcn_sdot4((int)((w[k] >> 4) & 0x0F0F0F0Fu), hq[2 * k + 1], s1, false);
;           }
;           const int sI = wave_sum_i(s0 + s1);
;           if (lane == e + u) acti = sI;
;         }
;       }
;       const float act = ((float)acti - 7.5f * (float)hsum) * sh * (hf == 0 ? ds0 : ds1);
;       gg[hf] *= 0.5f * act * (1.f + erff(act * 0.70710678118654752f)) * (hf == 0 ? us0 : us1);
.LBB0_854:
	s_andn2_saveexec_b64 s[0:1], s[0:1]
	v_mul_f32_e32 v19, v16, v16
	v_fmamk_f32 v21, v19, 0xba1345e1, v99
	v_fmaak_f32 v21, v19, v21, 0xbcdac9b8
	v_fmaak_f32 v21, v19, v21, 0x3de703be
	v_fmaak_f32 v21, v19, v21, 0xbec09330
	v_fmaak_f32 v19, v19, v21, 0x3e0375d0
	v_fma_f32 v19, |v16|, v19, |v16|
	s_or_b64 exec, exec, s[0:1]
	v_mul_f32_e32 v21, 0x40f00000, v22
	v_mov_b32_e32 v22, 0
	s_mov_b32 s4, 0
	v_readlane_b32 s0, v82, s4
	s_ashr_i32 s1, s0, 31
	s_lshl_b64 s[0:1], s[0:1], 10
	v_lshl_add_u64 v[52:53], v[66:67], 0, s[0:1]
	global_load_dwordx4 v[52:55], v[52:53], off
	s_add_i32 s5, s4, 1
	s_add_i32 s29, s4, 2
	s_add_i32 s30, s4, 3
	s_add_i32 s31, s4, 4
	s_add_i32 s33, s4, 5
	s_add_i32 s34, s4, 6
	s_add_i32 s35, s4, 7
	s_add_i32 s36, s4, 8
	s_add_i32 s37, s4, 9
	s_add_i32 s38, s4, 10
	s_add_i32 s39, s4, 11
	s_add_i32 s40, s4, 12
	s_add_i32 s41, s4, 13
	s_add_i32 s42, s4, 14
	s_add_i32 s43, s4, 15
	v_readlane_b32 s46, v82, s5
	v_readlane_b32 s48, v82, s29
	v_readlane_b32 s50, v82, s30
	v_readlane_b32 s52, v82, s31
	v_readlane_b32 s54, v82, s33
	v_readlane_b32 s56, v82, s34
	v_readlane_b32 s58, v82, s35
	v_readlane_b32 s60, v82, s36
	v_readlane_b32 s62, v82, s37
	v_readlane_b32 s64, v82, s38
	v_readlane_b32 s66, v82, s39
	v_readlane_b32 s68, v82, s40
	v_readlane_b32 s70, v82, s41
	v_readlane_b32 s72, v82, s42
	v_readlane_b32 s74, v82, s43
	s_ashr_i32 s47, s46, 31
	s_ashr_i32 s49, s48, 31
	s_ashr_i32 s51, s50, 31
	s_ashr_i32 s53, s52, 31
	s_ashr_i32 s55, s54, 31
	s_ashr_i32 s57, s56, 31
	s_ashr_i32 s59, s58, 31
	s_ashr_i32 s61, s60, 31
	s_ashr_i32 s63, s62, 31
	s_ashr_i32 s65, s64, 31
	s_ashr_i32 s67, s66, 31
	s_ashr_i32 s69, s68, 31
	s_ashr_i32 s71, s70, 31
	s_ashr_i32 s73, s72, 31
	s_ashr_i32 s75, s74, 31
	s_lshl_b64 s[0:1], s[46:47], 10
	s_lshl_b64 s[46:47], s[48:49], 10
	s_lshl_b64 s[48:49], s[50:51], 10
	s_lshl_b64 s[50:51], s[52:53], 10
	s_lshl_b64 s[52:53], s[54:55], 10
	s_lshl_b64 s[54:55], s[56:57], 10
	s_lshl_b64 s[56:57], s[58:59], 10
	s_lshl_b64 s[58:59], s[60:61], 10
	s_lshl_b64 s[60:61], s[62:63], 10
	s_lshl_b64 s[62:63], s[64:65], 10
	s_lshl_b64 s[64:65], s[66:67], 10
	s_lshl_b64 s[66:67], s[68:69], 10
	s_lshl_b64 s[68:69], s[70:71], 10
	s_lshl_b64 s[70:71], s[72:73], 10
	s_lshl_b64 s[72:73], s[74:75], 10
	v_lshl_add_u64 v[56:57], v[66:67], 0, s[0:1]
	v_lshl_add_u64 v[60:61], v[66:67], 0, s[46:47]
	v_lshl_add_u64 v[104:105], v[66:67], 0, s[48:49]
	v_lshl_add_u64 v[108:109], v[66:67], 0, s[50:51]
	v_lshl_add_u64 v[112:113], v[66:67], 0, s[52:53]
	v_lshl_add_u64 v[116:117], v[66:67], 0, s[54:55]
	v_lshl_add_u64 v[120:121], v[66:67], 0, s[56:57]
	v_lshl_add_u64 v[124:125], v[66:67], 0, s[58:59]
	v_lshl_add_u64 v[128:129], v[66:67], 0, s[60:61]
	v_lshl_add_u64 v[132:133], v[66:67], 0, s[62:63]
	v_lshl_add_u64 v[136:137], v[66:67], 0, s[64:65]
	v_lshl_add_u64 v[140:141], v[66:67], 0, s[66:67]
	v_lshl_add_u64 v[144:145], v[66:67], 0, s[68:69]
	v_lshl_add_u64 v[148:149], v[66:67], 0, s[70:71]
	v_lshl_add_u64 v[152:153], v[66:67], 0, s[72:73]
	global_load_dwordx4 v[56:59], v[56:57], off
	s_nop 0
	global_load_dwordx4 v[60:63], v[60:61], off
	s_nop 0
	global_load_dwordx4 v[104:107], v[104:105], off
	s_nop 0
	global_load_dwordx4 v[108:111], v[108:109], off
	s_nop 0
	global_load_dwordx4 v[112:115], v[112:113], off
	s_nop 0
	global_load_dwordx4 v[116:119], v[116:117], off
	s_nop 0
	global_load_dwordx4 v[120:123], v[120:121], off
	s_nop 0
	global_load_dwordx4 v[124:127], v[124:125], off
	s_nop 0
	global_load_dwordx4 v[128:131], v[128:129], off
	s_nop 0
	global_load_dwordx4 v[132:135], v[132:133], off
	s_nop 0
	global_load_dwordx4 v[136:139], v[136:137], off
	s_nop 0
	global_load_dwordx4 v[140:143], v[140:141], off
	s_nop 0
	global_load_dwordx4 v[144:147], v[144:145], off
	s_nop 0
	global_load_dwordx4 v[148:151], v[148:149], off
	s_nop 0
	global_load_dwordx4 v[152:155], v[152:153], off
.LBB0_857:
	v_mov_b32_e32 v23, 0
	v_mov_b32_e32 v24, 0
	v_mov_b32_e32 v25, 0
	s_waitcnt vmcnt(15)
	v_and_b32_e32 v87, 0xf0f0f0f, v52
	v_lshrrev_b32_e32 v52, 4, v52
	v_and_b32_e32 v103, 0xf0f0f0f, v53
	v_lshrrev_b32_e32 v53, 4, v53
	v_dot4c_i32_i8_e32 v23, v87, v5
	v_and_b32_e32 v52, 0xf0f0f0f, v52
	v_mov_b32_e32 v26, 0
	v_and_b32_e32 v156, 0xf0f0f0f, v54
	v_lshrrev_b32_e32 v54, 4, v54
	v_and_b32_e32 v53, 0xf0f0f0f, v53
	v_dot4c_i32_i8_e32 v24, v52, v6
	v_mov_b32_e32 v27, 0
	v_mov_b32_e32 v28, 0
	v_mov_b32_e32 v31, 0
	v_mov_b32_e32 v32, 0
	v_mov_b32_e32 v39, 0
	v_mov_b32_e32 v40, 0
	v_and_b32_e32 v157, 0xf0f0f0f, v55
	v_lshrrev_b32_e32 v55, 4, v55
	v_and_b32_e32 v54, 0xf0f0f0f, v54
	v_dot4c_i32_i8_e32 v23, v103, v7
	v_dot4c_i32_i8_e32 v24, v53, v8
	v_mov_b32_e32 v29, 0
	v_mov_b32_e32 v30, 0
	v_mov_b32_e32 v33, 0
	v_mov_b32_e32 v34, 0
	v_mov_b32_e32 v41, 0
	v_mov_b32_e32 v42, 0
	v_and_b32_e32 v55, 0xf0f0f0f, v55
	v_dot4c_i32_i8_e32 v23, v156, v9
	v_dot4c_i32_i8_e32 v24, v54, v10
	v_dot4c_i32_i8_e32 v23, v157, v11
	v_dot4c_i32_i8_e32 v24, v55, v12
	v_mov_b32_e32 v43, 0
	v_mov_b32_e32 v44, 0
	v_mov_b32_e32 v35, 0
	v_add_u32_e32 v23, v24, v23
	v_mov_b32_e32 v36, 0
	v_mov_b32_e32 v37, 0
	v_mov_b32_e32 v38, 0
	v_mov_b32_e32 v45, 0
	v_mov_b32_e32 v46, 0
	v_mov_b32_e32 v47, 0
	v_mov_b32_e32 v48, 0
	v_mov_b32_e32 v49, 0
	v_mov_b32_e32 v50, 0
	v_mov_b32_e32 v51, 0
	v_mov_b32_e32 v77, 0
	v_mov_b32_e32 v79, 0
	v_mov_b32_e32 v83, 0
	s_cmp_lt_u32 s4, 48
	s_waitcnt vmcnt(14)
	v_and_b32_e32 v87, 0xf0f0f0f, v56
	v_lshrrev_b32_e32 v56, 4, v56
	v_and_b32_e32 v158, 0xf0f0f0f, v57
	v_lshrrev_b32_e32 v57, 4, v57
	v_and_b32_e32 v159, 0xf0f0f0f, v58
	v_lshrrev_b32_e32 v58, 4, v58
	v_and_b32_e32 v160, 0xf0f0f0f, v59
	v_lshrrev_b32_e32 v59, 4, v59
	s_waitcnt vmcnt(13)
; __device__ void peer_phase(const Params& p) {
;     ...
;         for (int u = 0; u < 16; ++u) {
;           const u32 w[4] = {d[u].x, d[u].y, d[u].z, d[u].w};
;           int s0 = 0, s1 = 0;
; #pragma unroll
;           for (int k = 0; k < 4; ++k) {
;             s0 = __builtin_amdgcn_sdot4((int)(w[k] & 0x0F0F0F0Fu), hq[2 * k], s0, false);
;             s1 = __builtin_amdgcn_sdot4((int)((w[k] >> 4) & 0x0F0F0F0Fu), hq[2 * k + 1], s1, false);
;           }
	v_and_b32_e32 v161, 0xf0f0f0f, v60
	v_lshrrev_b32_e32 v60, 4, v60
	s_waitcnt vmcnt(12)
	v_and_b32_e32 v166, 0xf0f0f0f, v105
	v_lshrrev_b32_e32 v105, 4, v105
	v_and_b32_e32 v167, 0xf0f0f0f, v106
	v_lshrrev_b32_e32 v106, 4, v106
	s_waitcnt vmcnt(11)
	v_and_b32_e32 v169, 0xf0f0f0f, v108
	v_lshrrev_b32_e32 v108, 4, v108
	v_and_b32_e32 v170, 0xf0f0f0f, v109
	v_lshrrev_b32_e32 v109, 4, v109
	s_waitcnt vmcnt(10)
	v_and_b32_e32 v173, 0xf0f0f0f, v112
	v_lshrrev_b32_e32 v112, 4, v112
	v_and_b32_e32 v176, 0xf0f0f0f, v115
	v_lshrrev_b32_e32 v115, 4, v115
	s_waitcnt vmcnt(9)
	v_and_b32_e32 v179, 0xf0f0f0f, v118
	v_lshrrev_b32_e32 v118, 4, v118
	s_waitcnt vmcnt(8)
	v_and_b32_e32 v182, 0xf0f0f0f, v121
	v_lshrrev_b32_e32 v121, 4, v121
	s_waitcnt vmcnt(7)
	v_and_b32_e32 v185, 0xf0f0f0f, v124
	v_lshrrev_b32_e32 v124, 4, v124
	v_and_b32_e32 v52, 0xf0f0f0f, v56
	v_and_b32_e32 v162, 0xf0f0f0f, v61
	v_lshrrev_b32_e32 v61, 4, v61
	v_and_b32_e32 v163, 0xf0f0f0f, v62
	v_lshrrev_b32_e32 v62, 4, v62
	v_and_b32_e32 v164, 0xf0f0f0f, v63
	v_lshrrev_b32_e32 v63, 4, v63
	v_and_b32_e32 v165, 0xf0f0f0f, v104
	v_lshrrev_b32_e32 v104, 4, v104
	v_and_b32_e32 v168, 0xf0f0f0f, v107
	v_lshrrev_b32_e32 v107, 4, v107
	v_and_b32_e32 v171, 0xf0f0f0f, v110
	v_lshrrev_b32_e32 v110, 4, v110
	v_and_b32_e32 v174, 0xf0f0f0f, v113
	v_lshrrev_b32_e32 v113, 4, v113
	v_and_b32_e32 v177, 0xf0f0f0f, v116
	v_lshrrev_b32_e32 v116, 4, v116
	v_and_b32_e32 v180, 0xf0f0f0f, v119
	v_lshrrev_b32_e32 v119, 4, v119
	v_and_b32_e32 v183, 0xf0f0f0f, v122
	v_lshrrev_b32_e32 v122, 4, v122
	v_and_b32_e32 v186, 0xf0f0f0f, v125
	v_lshrrev_b32_e32 v125, 4, v125
	s_waitcnt vmcnt(6)
	v_and_b32_e32 v189, 0xf0f0f0f, v128
	v_lshrrev_b32_e32 v128, 4, v128
	v_dot4c_i32_i8_e32 v25, v87, v5
	v_and_b32_e32 v56, 0xf0f0f0f, v57
	v_and_b32_e32 v57, 0xf0f0f0f, v58
	v_and_b32_e32 v58, 0xf0f0f0f, v59
	v_and_b32_e32 v59, 0xf0f0f0f, v60
	v_and_b32_e32 v87, 0xf0f0f0f, v105
	v_and_b32_e32 v103, 0xf0f0f0f, v106
	v_and_b32_e32 v105, 0xf0f0f0f, v108
	v_and_b32_e32 v106, 0xf0f0f0f, v109
	v_and_b32_e32 v109, 0xf0f0f0f, v112
	v_and_b32_e32 v112, 0xf0f0f0f, v115
	v_and_b32_e32 v115, 0xf0f0f0f, v118
	v_and_b32_e32 v118, 0xf0f0f0f, v121
	v_and_b32_e32 v121, 0xf0f0f0f, v124
	v_dot4c_i32_i8_e32 v26, v52, v6
	v_and_b32_e32 v172, 0xf0f0f0f, v111
	v_lshrrev_b32_e32 v111, 4, v111
	v_and_b32_e32 v175, 0xf0f0f0f, v114
	v_lshrrev_b32_e32 v114, 4, v114
	v_and_b32_e32 v178, 0xf0f0f0f, v117
	v_lshrrev_b32_e32 v117, 4, v117
	v_and_b32_e32 v181, 0xf0f0f0f, v120
	v_lshrrev_b32_e32 v120, 4, v120
	v_and_b32_e32 v184, 0xf0f0f0f, v123
	v_lshrrev_b32_e32 v123, 4, v123
	v_and_b32_e32 v187, 0xf0f0f0f, v126
	v_lshrrev_b32_e32 v126, 4, v126
	v_and_b32_e32 v190, 0xf0f0f0f, v129
	v_lshrrev_b32_e32 v129, 4, v129
	v_dot4c_i32_i8_e32 v27, v161, v5
	v_and_b32_e32 v60, 0xf0f0f0f, v61
	v_and_b32_e32 v61, 0xf0f0f0f, v62
	v_and_b32_e32 v62, 0xf0f0f0f, v63
	v_and_b32_e32 v63, 0xf0f0f0f, v104
	v_and_b32_e32 v104, 0xf0f0f0f, v107
	v_dot4c_i32_i8_e32 v31, v169, v5
	v_and_b32_e32 v107, 0xf0f0f0f, v110
	v_and_b32_e32 v110, 0xf0f0f0f, v113
	v_and_b32_e32 v113, 0xf0f0f0f, v116
	v_and_b32_e32 v116, 0xf0f0f0f, v119
	v_and_b32_e32 v119, 0xf0f0f0f, v122
	v_dot4c_i32_i8_e32 v39, v185, v5
	v_and_b32_e32 v122, 0xf0f0f0f, v125
	v_and_b32_e32 v125, 0xf0f0f0f, v128
	v_dot4c_i32_i8_e32 v25, v158, v7
	v_dot4c_i32_i8_e32 v28, v59, v6
	v_dot4c_i32_i8_e32 v32, v105, v6
	v_dot4c_i32_i8_e32 v40, v121, v6
	v_dot4c_i32_i8_e32 v26, v56, v8
	v_and_b32_e32 v188, 0xf0f0f0f, v127
	v_lshrrev_b32_e32 v127, 4, v127
	v_and_b32_e32 v191, 0xf0f0f0f, v130
	v_lshrrev_b32_e32 v130, 4, v130
	s_waitcnt vmcnt(5)
	v_and_b32_e32 v193, 0xf0f0f0f, v132
	v_lshrrev_b32_e32 v132, 4, v132
	v_dot4c_i32_i8_e32 v29, v165, v5
	v_and_b32_e32 v108, 0xf0f0f0f, v111
	v_dot4c_i32_i8_e32 v33, v173, v5
	v_and_b32_e32 v111, 0xf0f0f0f, v114
	v_and_b32_e32 v114, 0xf0f0f0f, v117
	v_and_b32_e32 v117, 0xf0f0f0f, v120
	v_and_b32_e32 v120, 0xf0f0f0f, v123
	v_and_b32_e32 v123, 0xf0f0f0f, v126
	v_dot4c_i32_i8_e32 v41, v189, v5
	v_and_b32_e32 v126, 0xf0f0f0f, v129
	v_dot4c_i32_i8_e32 v27, v162, v7
	v_dot4c_i32_i8_e32 v30, v63, v6
	v_dot4c_i32_i8_e32 v31, v170, v7
	v_dot4c_i32_i8_e32 v34, v109, v6
	v_dot4c_i32_i8_e32 v39, v186, v7
	v_dot4c_i32_i8_e32 v42, v125, v6
	v_dot4c_i32_i8_e32 v25, v159, v9
	v_dot4c_i32_i8_e32 v28, v60, v8
	v_dot4c_i32_i8_e32 v32, v106, v8
	v_dot4c_i32_i8_e32 v40, v122, v8
	v_dot4c_i32_i8_e32 v26, v57, v10
	v_and_b32_e32 v192, 0xf0f0f0f, v131
	v_lshrrev_b32_e32 v131, 4, v131
	v_and_b32_e32 v194, 0xf0f0f0f, v133
	v_lshrrev_b32_e32 v133, 4, v133
	v_and_b32_e32 v124, 0xf0f0f0f, v127
	v_and_b32_e32 v127, 0xf0f0f0f, v130
	v_and_b32_e32 v129, 0xf0f0f0f, v132
	v_dot4c_i32_i8_e32 v29, v166, v7
	v_dot4c_i32_i8_e32 v33, v174, v7
	v_dot4c_i32_i8_e32 v41, v190, v7
	v_dot4c_i32_i8_e32 v27, v163, v9
	v_dot4c_i32_i8_e32 v30, v87, v8
	v_dot4c_i32_i8_e32 v31, v171, v9
	v_dot4c_i32_i8_e32 v34, v110, v8
	v_dot4c_i32_i8_e32 v39, v187, v9
	v_dot4c_i32_i8_e32 v42, v126, v8
	v_dot4c_i32_i8_e32 v25, v160, v11
	v_dot4c_i32_i8_e32 v28, v61, v10
	v_dot4c_i32_i8_e32 v32, v107, v10
	v_dot4c_i32_i8_e32 v40, v123, v10
	v_dot4c_i32_i8_e32 v26, v58, v12
	v_and_b32_e32 v195, 0xf0f0f0f, v134
	v_lshrrev_b32_e32 v134, 4, v134
	s_waitcnt vmcnt(4)
; __device__ void peer_phase(const Params& p) {
;     ...
;         for (int u = 0; u < 16; ++u) {
;           const u32 w[4] = {d[u].x, d[u].y, d[u].z, d[u].w};
;           int s0 = 0, s1 = 0;
; #pragma unroll
;           for (int k = 0; k < 4; ++k) {
;             s0 = __builtin_amdgcn_sdot4((int)(w[k] & 0x0F0F0F0Fu), hq[2 * k], s0, false);
;             s1 = __builtin_amdgcn_sdot4((int)((w[k] >> 4) & 0x0F0F0F0Fu), hq[2 * k + 1], s1, false);
;           }
;           const int sI = wave_sum_i(s0 + s1);
;           if (lane == e + u) acti = sI;
	v_and_b32_e32 v197, 0xf0f0f0f, v136
	v_lshrrev_b32_e32 v136, 4, v136
	v_and_b32_e32 v128, 0xf0f0f0f, v131
	v_dot4c_i32_i8_e32 v43, v193, v5
	v_and_b32_e32 v130, 0xf0f0f0f, v133
	v_dot4c_i32_i8_e32 v44, v129, v6
	v_dot4c_i32_i8_e32 v29, v167, v9
	v_dot4c_i32_i8_e32 v33, v175, v9
	v_dot4c_i32_i8_e32 v41, v191, v9
	v_dot4c_i32_i8_e32 v27, v164, v11
	v_dot4c_i32_i8_e32 v30, v103, v10
	v_dot4c_i32_i8_e32 v31, v172, v11
	v_dot4c_i32_i8_e32 v34, v111, v10
	v_dot4c_i32_i8_e32 v39, v188, v11
	v_dot4c_i32_i8_e32 v42, v127, v10
	v_dot4c_i32_i8_e32 v28, v62, v12
	v_dot4c_i32_i8_e32 v32, v108, v12
	v_dot4c_i32_i8_e32 v40, v124, v12
	v_add_u32_e32 v25, v26, v25
	v_and_b32_e32 v196, 0xf0f0f0f, v135
	v_lshrrev_b32_e32 v135, 4, v135
	v_and_b32_e32 v198, 0xf0f0f0f, v137
	v_lshrrev_b32_e32 v137, 4, v137
	v_dot4c_i32_i8_e32 v35, v177, v5
	v_and_b32_e32 v131, 0xf0f0f0f, v134
	v_and_b32_e32 v133, 0xf0f0f0f, v136
	v_dot4c_i32_i8_e32 v36, v113, v6
	v_dot4c_i32_i8_e32 v43, v194, v7
	v_dot4c_i32_i8_e32 v44, v130, v8
	v_dot4c_i32_i8_e32 v29, v168, v11
	v_dot4c_i32_i8_e32 v33, v176, v11
	v_dot4c_i32_i8_e32 v41, v192, v11
	v_dot4c_i32_i8_e32 v30, v104, v12
	v_dot4c_i32_i8_e32 v34, v112, v12
	v_dot4c_i32_i8_e32 v42, v128, v12
	v_add_u32_e32 v26, v28, v27
	v_add_u32_e32 v28, v32, v31
	v_add_u32_e32 v32, v40, v39
	v_and_b32_e32 v199, 0xf0f0f0f, v138
	v_lshrrev_b32_e32 v138, 4, v138
	s_waitcnt vmcnt(3)
	v_and_b32_e32 v201, 0xf0f0f0f, v140
	v_lshrrev_b32_e32 v140, 4, v140
	v_dot4c_i32_i8_e32 v37, v181, v5
	v_and_b32_e32 v132, 0xf0f0f0f, v135
	v_dot4c_i32_i8_e32 v45, v197, v5
	v_and_b32_e32 v134, 0xf0f0f0f, v137
	v_dot4c_i32_i8_e32 v35, v178, v7
	v_dot4c_i32_i8_e32 v38, v117, v6
	v_dot4c_i32_i8_e32 v46, v133, v6
	v_dot4c_i32_i8_e32 v36, v114, v8
	v_dot4c_i32_i8_e32 v43, v195, v9
	v_dot4c_i32_i8_e32 v44, v131, v10
	v_add_u32_e32 v27, v30, v29
	v_add_u32_e32 v29, v34, v33
	v_add_u32_e32 v33, v42, v41
	v_and_b32_e32 v200, 0xf0f0f0f, v139
	v_lshrrev_b32_e32 v139, 4, v139
	v_and_b32_e32 v202, 0xf0f0f0f, v141
	v_lshrrev_b32_e32 v141, 4, v141
	v_and_b32_e32 v135, 0xf0f0f0f, v138
	v_and_b32_e32 v137, 0xf0f0f0f, v140
	v_dot4c_i32_i8_e32 v37, v182, v7
	v_dot4c_i32_i8_e32 v45, v198, v7
	v_dot4c_i32_i8_e32 v35, v179, v9
	v_dot4c_i32_i8_e32 v38, v118, v8
	v_dot4c_i32_i8_e32 v46, v134, v8
	v_dot4c_i32_i8_e32 v36, v115, v10
	v_dot4c_i32_i8_e32 v43, v196, v11
	v_dot4c_i32_i8_e32 v44, v132, v12
	v_and_b32_e32 v203, 0xf0f0f0f, v142
	v_lshrrev_b32_e32 v142, 4, v142
	s_waitcnt vmcnt(2)
	v_and_b32_e32 v205, 0xf0f0f0f, v144
	v_lshrrev_b32_e32 v144, 4, v144
	v_and_b32_e32 v136, 0xf0f0f0f, v139
	v_dot4c_i32_i8_e32 v47, v201, v5
	v_and_b32_e32 v138, 0xf0f0f0f, v141
	v_dot4c_i32_i8_e32 v48, v137, v6
	v_dot4c_i32_i8_e32 v37, v183, v9
	v_dot4c_i32_i8_e32 v45, v199, v9
	v_dot4c_i32_i8_e32 v35, v180, v11
	v_dot4c_i32_i8_e32 v38, v119, v10
	v_dot4c_i32_i8_e32 v46, v135, v10
	v_dot4c_i32_i8_e32 v36, v116, v12
	v_add_u32_e32 v34, v44, v43
	v_and_b32_e32 v204, 0xf0f0f0f, v143
	v_lshrrev_b32_e32 v143, 4, v143
	v_and_b32_e32 v206, 0xf0f0f0f, v145
	v_lshrrev_b32_e32 v145, 4, v145
	v_and_b32_e32 v139, 0xf0f0f0f, v142
	v_and_b32_e32 v141, 0xf0f0f0f, v144
	v_dot4c_i32_i8_e32 v47, v202, v7
	v_dot4c_i32_i8_e32 v48, v138, v8
	v_dot4c_i32_i8_e32 v37, v184, v11
	v_dot4c_i32_i8_e32 v45, v200, v11
	v_dot4c_i32_i8_e32 v38, v120, v12
	v_dot4c_i32_i8_e32 v46, v136, v12
	v_add_u32_e32 v30, v36, v35
	v_and_b32_e32 v207, 0xf0f0f0f, v146
	v_lshrrev_b32_e32 v146, 4, v146
	s_waitcnt vmcnt(1)
	v_and_b32_e32 v209, 0xf0f0f0f, v148
	v_lshrrev_b32_e32 v148, 4, v148
	v_and_b32_e32 v140, 0xf0f0f0f, v143
	v_dot4c_i32_i8_e32 v49, v205, v5
	v_and_b32_e32 v142, 0xf0f0f0f, v145
	v_dot4c_i32_i8_e32 v50, v141, v6
	v_dot4c_i32_i8_e32 v47, v203, v9
	v_dot4c_i32_i8_e32 v48, v139, v10
	v_add_u32_e32 v31, v38, v37
	v_add_u32_e32 v35, v46, v45
	v_and_b32_e32 v208, 0xf0f0f0f, v147
	v_lshrrev_b32_e32 v147, 4, v147
	v_and_b32_e32 v210, 0xf0f0f0f, v149
	v_lshrrev_b32_e32 v149, 4, v149
	v_and_b32_e32 v143, 0xf0f0f0f, v146
	v_and_b32_e32 v145, 0xf0f0f0f, v148
	v_dot4c_i32_i8_e32 v49, v206, v7
	v_dot4c_i32_i8_e32 v50, v142, v8
	v_dot4c_i32_i8_e32 v47, v204, v11
	v_dot4c_i32_i8_e32 v48, v140, v12
	v_and_b32_e32 v211, 0xf0f0f0f, v150
	v_lshrrev_b32_e32 v150, 4, v150
	s_waitcnt vmcnt(0)
	v_and_b32_e32 v213, 0xf0f0f0f, v152
	v_lshrrev_b32_e32 v152, 4, v152
	v_and_b32_e32 v144, 0xf0f0f0f, v147
	v_dot4c_i32_i8_e32 v51, v209, v5
	v_and_b32_e32 v146, 0xf0f0f0f, v149
	v_dot4c_i32_i8_e32 v77, v145, v6
	v_dot4c_i32_i8_e32 v49, v207, v9
	v_dot4c_i32_i8_e32 v50, v143, v10
	v_add_u32_e32 v36, v48, v47
	v_and_b32_e32 v212, 0xf0f0f0f, v151
	v_lshrrev_b32_e32 v151, 4, v151
	v_and_b32_e32 v214, 0xf0f0f0f, v153
	v_lshrrev_b32_e32 v153, 4, v153
	v_and_b32_e32 v147, 0xf0f0f0f, v150
	v_and_b32_e32 v149, 0xf0f0f0f, v152
	v_dot4c_i32_i8_e32 v51, v210, v7
	v_dot4c_i32_i8_e32 v77, v146, v8
	v_dot4c_i32_i8_e32 v49, v208, v11
	v_dot4c_i32_i8_e32 v50, v144, v12
	v_and_b32_e32 v215, 0xf0f0f0f, v154
	v_lshrrev_b32_e32 v154, 4, v154
	v_and_b32_e32 v148, 0xf0f0f0f, v151
	v_dot4c_i32_i8_e32 v79, v213, v5
	v_and_b32_e32 v150, 0xf0f0f0f, v153
	v_dot4c_i32_i8_e32 v83, v149, v6
	v_dot4c_i32_i8_e32 v51, v211, v9
	v_dot4c_i32_i8_e32 v77, v147, v10
	v_add_u32_e32 v37, v50, v49
	v_and_b32_e32 v216, 0xf0f0f0f, v155
	v_lshrrev_b32_e32 v155, 4, v155
	v_and_b32_e32 v151, 0xf0f0f0f, v154
	v_dot4c_i32_i8_e32 v79, v214, v7
	v_dot4c_i32_i8_e32 v83, v150, v8
	v_dot4c_i32_i8_e32 v51, v212, v11
	v_dot4c_i32_i8_e32 v77, v148, v12
	v_and_b32_e32 v152, 0xf0f0f0f, v155
	v_dot4c_i32_i8_e32 v79, v215, v9
	v_dot4c_i32_i8_e32 v83, v151, v10
	v_add_u32_e32 v38, v77, v51
	v_dot4c_i32_i8_e32 v79, v216, v11
	v_dot4c_i32_i8_e32 v83, v152, v12
	s_nop 2
	v_add_u32_e32 v39, v83, v79
	s_add_i32 s4, s4, 16
	s_cmp_gt_u32 s4, 63
	s_cbranch_scc1 .Lp9_dskip2
; __device__ void peer_phase(const Params& p) {
;     ...
;       for (int e = 0; e < 64; e += 16) {
;         uint4 d[16];
; #pragma unroll
;         for (int u = 0; u < 16; ++u) {
;           const int id = __builtin_amdgcn_readlane(eid[hf], e + u);
;           d[u] = ((const uint4*)(down4 + (size_t)id * 1024))[lane];
;         }
	s_nop 3
	v_readlane_b32 s0, v82, s4
	s_ashr_i32 s1, s0, 31
	s_lshl_b64 s[0:1], s[0:1], 10
	v_lshl_add_u64 v[52:53], v[66:67], 0, s[0:1]
	global_load_dwordx4 v[52:55], v[52:53], off
	s_add_i32 s5, s4, 1
	s_add_i32 s29, s4, 2
	s_add_i32 s30, s4, 3
	s_add_i32 s31, s4, 4
	s_add_i32 s33, s4, 5
	s_add_i32 s34, s4, 6
	s_add_i32 s35, s4, 7
	s_add_i32 s36, s4, 8
	s_add_i32 s37, s4, 9
	s_add_i32 s38, s4, 10
	s_add_i32 s39, s4, 11
	s_add_i32 s40, s4, 12
	s_add_i32 s41, s4, 13
	s_add_i32 s42, s4, 14
	s_add_i32 s43, s4, 15
	v_readlane_b32 s46, v82, s5
	v_readlane_b32 s48, v82, s29
	v_readlane_b32 s50, v82, s30
	v_readlane_b32 s52, v82, s31
	v_readlane_b32 s54, v82, s33
	v_readlane_b32 s56, v82, s34
	v_readlane_b32 s58, v82, s35
	v_readlane_b32 s60, v82, s36
	v_readlane_b32 s62, v82, s37
	v_readlane_b32 s64, v82, s38
	v_readlane_b32 s66, v82, s39
	v_readlane_b32 s68, v82, s40
	v_readlane_b32 s70, v82, s41
	v_readlane_b32 s72, v82, s42
	v_readlane_b32 s74, v82, s43
	s_ashr_i32 s47, s46, 31
	s_ashr_i32 s49, s48, 31
	s_ashr_i32 s51, s50, 31
	s_ashr_i32 s53, s52, 31
	s_ashr_i32 s55, s54, 31
	s_ashr_i32 s57, s56, 31
	s_ashr_i32 s59, s58, 31
	s_ashr_i32 s61, s60, 31
	s_ashr_i32 s63, s62, 31
	s_ashr_i32 s65, s64, 31
	s_ashr_i32 s67, s66, 31
	s_ashr_i32 s69, s68, 31
	s_ashr_i32 s71, s70, 31
	s_ashr_i32 s73, s72, 31
	s_ashr_i32 s75, s74, 31
	s_lshl_b64 s[0:1], s[46:47], 10
	s_lshl_b64 s[46:47], s[48:49], 10
	s_lshl_b64 s[48:49], s[50:51], 10
	s_lshl_b64 s[50:51], s[52:53], 10
	s_lshl_b64 s[52:53], s[54:55], 10
	s_lshl_b64 s[54:55], s[56:57], 10
	s_lshl_b64 s[56:57], s[58:59], 10
	s_lshl_b64 s[58:59], s[60:61], 10
	s_lshl_b64 s[60:61], s[62:63], 10
	s_lshl_b64 s[62:63], s[64:65], 10
	s_lshl_b64 s[64:65], s[66:67], 10
	s_lshl_b64 s[66:67], s[68:69], 10
	s_lshl_b64 s[68:69], s[70:71], 10
	s_lshl_b64 s[70:71], s[72:73], 10
	s_lshl_b64 s[72:73], s[74:75], 10
	v_lshl_add_u64 v[56:57], v[66:67], 0, s[0:1]
	v_lshl_add_u64 v[60:61], v[66:67], 0, s[46:47]
	v_lshl_add_u64 v[104:105], v[66:67], 0, s[48:49]
	v_lshl_add_u64 v[108:109], v[66:67], 0, s[50:51]
	v_lshl_add_u64 v[112:113], v[66:67], 0, s[52:53]
	v_lshl_add_u64 v[116:117], v[66:67], 0, s[54:55]
	v_lshl_add_u64 v[120:121], v[66:67], 0, s[56:57]
	v_lshl_add_u64 v[124:125], v[66:67], 0, s[58:59]
	v_lshl_add_u64 v[128:129], v[66:67], 0, s[60:61]
	v_lshl_add_u64 v[132:133], v[66:67], 0, s[62:63]
	v_lshl_add_u64 v[136:137], v[66:67], 0, s[64:65]
	v_lshl_add_u64 v[140:141], v[66:67], 0, s[66:67]
	v_lshl_add_u64 v[144:145], v[66:67], 0, s[68:69]
	v_lshl_add_u64 v[148:149], v[66:67], 0, s[70:71]
	v_lshl_add_u64 v[152:153], v[66:67], 0, s[72:73]
	global_load_dwordx4 v[56:59], v[56:57], off
	s_nop 0
	global_load_dwordx4 v[60:63], v[60:61], off
	s_nop 0
	global_load_dwordx4 v[104:107], v[104:105], off
	s_nop 0
	global_load_dwordx4 v[108:111], v[108:109], off
	s_nop 0
	global_load_dwordx4 v[112:115], v[112:113], off
	s_nop 0
	global_load_dwordx4 v[116:119], v[116:117], off
	s_nop 0
	global_load_dwordx4 v[120:123], v[120:121], off
	s_nop 0
	global_load_dwordx4 v[124:127], v[124:125], off
	s_nop 0
	global_load_dwordx4 v[128:131], v[128:129], off
	s_nop 0
	global_load_dwordx4 v[132:135], v[132:133], off
	s_nop 0
	global_load_dwordx4 v[136:139], v[136:137], off
	s_nop 0
	global_load_dwordx4 v[140:143], v[140:141], off
	s_nop 0
	global_load_dwordx4 v[144:147], v[144:145], off
	s_nop 0
	global_load_dwordx4 v[148:151], v[148:149], off
	s_nop 0
	global_load_dwordx4 v[152:155], v[152:153], off
; __device__ void peer_phase(const Params& p) {
;     ...
;           const int sI = wave_sum_i(s0 + s1);
;           if (lane == e + u) acti = sI;
;         }
;       }
;       const float act = ((float)acti - 7.5f * (float)hsum) * sh * (hf == 0 ? ds0 : ds1);
;       gg[hf] *= 0.5f * act * (1.f + erff(act * 0.70710678118654752f)) * (hf == 0 ? us0 : us1);
.Lp9_dskip2:
	s_add_i32 s44, s4, -16
	s_cmp_lt_u32 s44, 48
	s_nop 1
	v_add_u32_dpp v40, v23, v23 row_mirror row_mask:0xf bank_mask:0x3
	v_add_u32_dpp v40, v32, v32 row_mirror row_mask:0xf bank_mask:0xc
	v_add_u32_dpp v41, v25, v25 row_mirror row_mask:0xf bank_mask:0x3
	v_add_u32_dpp v41, v33, v33 row_mirror row_mask:0xf bank_mask:0xc
	v_add_u32_dpp v42, v26, v26 row_mirror row_mask:0xf bank_mask:0x3
	v_add_u32_dpp v42, v34, v34 row_mirror row_mask:0xf bank_mask:0xc
	v_add_u32_dpp v43, v27, v27 row_mirror row_mask:0xf bank_mask:0x3
	v_add_u32_dpp v43, v35, v35 row_mirror row_mask:0xf bank_mask:0xc
	v_add_u32_dpp v44, v28, v28 row_mirror row_mask:0xf bank_mask:0x3
	v_add_u32_dpp v44, v36, v36 row_mirror row_mask:0xf bank_mask:0xc
	v_add_u32_dpp v45, v29, v29 row_mirror row_mask:0xf bank_mask:0x3
	v_add_u32_dpp v45, v37, v37 row_mirror row_mask:0xf bank_mask:0xc
	v_add_u32_dpp v46, v30, v30 row_mirror row_mask:0xf bank_mask:0x3
	v_add_u32_dpp v46, v38, v38 row_mirror row_mask:0xf bank_mask:0xc
	v_add_u32_dpp v47, v31, v31 row_mirror row_mask:0xf bank_mask:0x3
	v_add_u32_dpp v47, v39, v39 row_mirror row_mask:0xf bank_mask:0xc
	v_add_u32_dpp v48, v40, v40 row_half_mirror row_mask:0xf bank_mask:0x5
	v_add_u32_dpp v48, v44, v44 row_half_mirror row_mask:0xf bank_mask:0xa
	v_add_u32_dpp v49, v41, v41 row_half_mirror row_mask:0xf bank_mask:0x5
	v_add_u32_dpp v49, v45, v45 row_half_mirror row_mask:0xf bank_mask:0xa
	v_add_u32_dpp v50, v42, v42 row_half_mirror row_mask:0xf bank_mask:0x5
	v_add_u32_dpp v50, v46, v46 row_half_mirror row_mask:0xf bank_mask:0xa
	v_add_u32_dpp v51, v43, v43 row_half_mirror row_mask:0xf bank_mask:0x5
	v_add_u32_dpp v51, v47, v47 row_half_mirror row_mask:0xf bank_mask:0xa
	v_add_u32_dpp v48, v48, v48 quad_perm:[1,0,3,2] row_mask:0xf bank_mask:0xf
	v_add_u32_dpp v49, v49, v49 quad_perm:[1,0,3,2] row_mask:0xf bank_mask:0xf
	v_add_u32_dpp v50, v50, v50 quad_perm:[1,0,3,2] row_mask:0xf bank_mask:0xf
	v_add_u32_dpp v51, v51, v51 quad_perm:[1,0,3,2] row_mask:0xf bank_mask:0xf
	v_add_u32_dpp v48, v48, v48 quad_perm:[2,3,0,1] row_mask:0xf bank_mask:0xf
	v_add_u32_dpp v49, v49, v49 quad_perm:[2,3,0,1] row_mask:0xf bank_mask:0xf
	v_add_u32_dpp v50, v50, v50 quad_perm:[2,3,0,1] row_mask:0xf bank_mask:0xf
	v_add_u32_dpp v51, v51, v51 quad_perm:[2,3,0,1] row_mask:0xf bank_mask:0xf
	s_mov_b32 vcc_lo, 0x22222222
	s_mov_b32 vcc_hi, 0x22222222
	s_nop 1
	v_cndmask_b32_e32 v48, v48, v49, vcc
	s_mov_b32 vcc_lo, 0x44444444
	s_mov_b32 vcc_hi, 0x44444444
	s_nop 1
	v_cndmask_b32_e32 v48, v48, v50, vcc
	s_mov_b32 vcc_lo, 0x88888888
	s_mov_b32 vcc_hi, 0x88888888
	s_nop 1
	v_cndmask_b32_e32 v48, v48, v51, vcc
	ds_bpermute_b32 v24, v90, v48
	v_and_b32_e32 v49, 48, v88
	v_cmp_eq_u32_e32 vcc, s44, v49
	s_waitcnt lgkmcnt(0)
	v_add_u32_e32 v48, v24, v48
	ds_bpermute_b32 v24, v89, v48
	s_waitcnt lgkmcnt(0)
	v_add_u32_e32 v48, v24, v48
	s_nop 1
	v_cndmask_b32_e32 v22, v22, v48, vcc
	s_cbranch_scc1 .LBB0_857
	v_cvt_f32_i32_e32 v5, v22
	v_sub_f32_e32 v5, v5, v21
	v_mul_f32_e32 v5, v20, v5
	v_mul_f32_e32 v5, v3, v5
	v_mul_f32_e32 v3, 0x3f3504f3, v5
	v_cmp_nlt_f32_e64 s[0:1], |v3|, 1.0
	s_and_saveexec_b64 s[4:5], s[0:1]
	s_xor_b64 s[0:1], exec, s[4:5]
	s_cbranch_execz .LBB0_860
	v_fma_f32 v6, |v3|, s12, v100
	v_fma_f32 v6, |v3|, v6, s13
	v_fma_f32 v6, |v3|, v6, s14
	v_fma_f32 v6, |v3|, v6, s15
	v_fma_f32 v6, |v3|, v6, s16
	v_fma_f32 v6, |v3|, v6, s17
	v_fma_f32 v6, |v3|, v6, |v3|
	v_mul_f32_e32 v7, 0xbfb8aa3b, v6
	v_fma_f32 v8, v6, s18, -v7
	v_rndne_f32_e32 v9, v7
	v_fmac_f32_e32 v8, 0xb2a5705f, v6
	v_sub_f32_e32 v7, v7, v9
	v_add_f32_e32 v7, v7, v8
	v_cvt_i32_f32_e32 v8, v9
	v_exp_f32_e32 v7, v7
	v_cmp_nlt_f32_e32 vcc, s19, v6
	v_ldexp_f32 v7, v7, v8
	s_nop 0
	v_cndmask_b32_e32 v7, 0, v7, vcc
	v_cmp_ngt_f32_e32 vcc, s20, v6
	s_nop 1
	v_cndmask_b32_e32 v6, v101, v7, vcc
	v_sub_f32_e32 v6, 1.0, v6
